# sigmoid-gate tiles of the input projection: hand-written epilogue (same math, no exec-mask branching / address rebuild per call)
# speedup vs baseline: 1.0083x; 1.0004x over previous
.LBB0_247:
	s_sub_u32 s98, s8, 0x200
	s_cmp_lt_u32 s98, 0x600
	s_cbranch_scc1 .Luhy_epi
	s_cmpk_ge_u32 s8, 0x800
	s_cbranch_scc1 .Lgate_epi
	v_add_u32_e32 v150, s4, v158
	v_ashrrev_i32_e32 v154, 11, v150
	v_add_u32_e32 v146, s8, v160
	v_ashrrev_i32_e32 v151, 31, v150
	v_ashrrev_i32_e32 v155, 31, v154
	v_and_b32_e32 v164, 0x7ff, v150
	v_lshlrev_b64 v[152:153], 12, v[150:151]
	v_lshlrev_b64 v[156:157], 12, v[154:155]
	v_cmp_lt_i32_e64 s[4:5], s71, v146
	s_and_saveexec_b64 s[2:3], s[4:5]
	s_xor_b64 s[8:9], exec, s[2:3]
	s_cbranch_execz .LBB0_253
	v_cmp_lt_u32_e32 vcc, s70, v146
	s_and_saveexec_b64 s[2:3], vcc
	s_xor_b64 s[40:41], exec, s[2:3]
	s_cbranch_execz .LBB0_250
	v_mul_f32_e32 v136, 0xbfb8aa3b, v124
	v_mul_f32_e32 v147, 0xbfb8aa3b, v120
	v_mul_f32_e32 v148, 0xbfb8aa3b, v125
	v_mul_f32_e32 v149, 0xbfb8aa3b, v121
	v_exp_f32_e32 v136, v136
	v_exp_f32_e32 v147, v147
	v_exp_f32_e32 v148, v148
	v_exp_f32_e32 v149, v149
	v_mul_f32_e32 v151, 0xbfb8aa3b, v126
	v_mul_f32_e32 v155, 0xbfb8aa3b, v122
	v_mul_f32_e32 v165, 0xbfb8aa3b, v127
	v_mul_f32_e32 v166, 0xbfb8aa3b, v123
	v_exp_f32_e32 v151, v151
	v_exp_f32_e32 v155, v155
	v_exp_f32_e32 v165, v165
	v_exp_f32_e32 v166, v166
	v_add_f32_e32 v136, 1.0, v136
	v_add_f32_e32 v147, 1.0, v147
	v_add_f32_e32 v148, 1.0, v148
	v_add_f32_e32 v149, 1.0, v149
	v_rcp_f32_e32 v136, v136
	v_rcp_f32_e32 v147, v147
	v_rcp_f32_e32 v148, v148
	v_rcp_f32_e32 v149, v149
	v_add_f32_e32 v151, 1.0, v151
	v_add_f32_e32 v155, 1.0, v155
	v_add_f32_e32 v165, 1.0, v165
	v_add_f32_e32 v166, 1.0, v166
	v_rcp_f32_e32 v151, v151
	v_rcp_f32_e32 v155, v155
	v_rcp_f32_e32 v165, v165
	v_rcp_f32_e32 v169, v166
	v_cvt_pk_bf16_f32 v166, v136, v148
	v_cvt_pk_bf16_f32 v168, v147, v149
	v_lshl_add_u64 v[148:149], s[24:25], 0, v[152:153]
	v_mov_b32_e32 v147, v137
	v_cvt_pk_bf16_f32 v167, v151, v165
	v_cvt_pk_bf16_f32 v169, v155, v169
	v_lshl_add_u64 v[148:149], v[146:147], 1, v[148:149]
	global_store_dwordx4 v[148:149], v[166:169], off offset:-4096 nt

.Lgate_epi:
	v_and_b32_e32 v136, 63, v193
	v_lshrrev_b32_e32 v156, 6, v193
	v_and_b32_e32 v146, 15, v136
	v_lshrrev_b32_e32 v147, 4, v136
	v_lshlrev_b32_e32 v147, 4, v147
	v_lshl_add_u32 v148, v146, 12, v147
	v_readfirstlane_b32 s98, v156
	s_nop 3
	s_and_b32 s99, s98, 3
	s_lshr_b32 s98, s98, 2
	s_lshl_b32 s99, s99, 6
	s_lshl_b32 s98, s98, 18
	s_add_i32 s98, s98, s99
	s_lshl_b32 s99, s4, 12
	s_add_i32 s98, s98, s99
	s_sub_i32 s99, s8, 0x800
	s_lshl_b32 s99, s99, 1
	s_add_i32 s98, s98, s99
	v_add_u32_e32 v148, s98, v148
	v_mov_b32_e32 v149, 0
	v_lshl_add_u64 v[148:149], s[24:25], 0, v[148:149]
	s_mov_b32 s101, 0
	v_mul_f32_e32 v124, 0xbfb8aa3b, v124
	v_mul_f32_e32 v125, 0xbfb8aa3b, v125
	v_mul_f32_e32 v126, 0xbfb8aa3b, v126
	v_mul_f32_e32 v127, 0xbfb8aa3b, v127
	v_mul_f32_e32 v120, 0xbfb8aa3b, v120
	v_mul_f32_e32 v121, 0xbfb8aa3b, v121
	v_mul_f32_e32 v122, 0xbfb8aa3b, v122
	v_mul_f32_e32 v123, 0xbfb8aa3b, v123
	v_exp_f32_e32 v124, v124
	v_exp_f32_e32 v125, v125
	v_exp_f32_e32 v126, v126
	v_exp_f32_e32 v127, v127
	v_exp_f32_e32 v120, v120
	v_exp_f32_e32 v121, v121
	v_exp_f32_e32 v122, v122
	v_exp_f32_e32 v123, v123
	v_add_f32_e32 v124, 1.0, v124
	v_add_f32_e32 v125, 1.0, v125
	v_add_f32_e32 v126, 1.0, v126
	v_add_f32_e32 v127, 1.0, v127
	v_add_f32_e32 v120, 1.0, v120
	v_add_f32_e32 v121, 1.0, v121
	v_add_f32_e32 v122, 1.0, v122
	v_add_f32_e32 v123, 1.0, v123
	v_rcp_f32_e32 v124, v124
	v_rcp_f32_e32 v125, v125
	v_rcp_f32_e32 v126, v126
	v_rcp_f32_e32 v127, v127
	v_rcp_f32_e32 v120, v120
	v_rcp_f32_e32 v121, v121
	v_rcp_f32_e32 v122, v122
	v_rcp_f32_e32 v123, v123
	v_cvt_pk_bf16_f32 v152, v124, v125
	v_cvt_pk_bf16_f32 v153, v126, v127
	v_cvt_pk_bf16_f32 v154, v120, v121
	s_nop 0
	v_cvt_pk_bf16_f32 v155, v122, v123
	global_store_dwordx4 v[148:149], v[152:155], off nt
	v_mul_f32_e32 v116, 0xbfb8aa3b, v116
	v_mul_f32_e32 v117, 0xbfb8aa3b, v117
	v_mul_f32_e32 v118, 0xbfb8aa3b, v118
	v_mul_f32_e32 v119, 0xbfb8aa3b, v119
	v_mul_f32_e32 v112, 0xbfb8aa3b, v112
	v_mul_f32_e32 v113, 0xbfb8aa3b, v113
	v_mul_f32_e32 v114, 0xbfb8aa3b, v114
	v_mul_f32_e32 v115, 0xbfb8aa3b, v115
	v_exp_f32_e32 v116, v116
	v_exp_f32_e32 v117, v117
	v_exp_f32_e32 v118, v118
	v_exp_f32_e32 v119, v119
	v_exp_f32_e32 v112, v112
	v_exp_f32_e32 v113, v113
	v_exp_f32_e32 v114, v114
	v_exp_f32_e32 v115, v115
	v_add_f32_e32 v116, 1.0, v116
	v_add_f32_e32 v117, 1.0, v117
	v_add_f32_e32 v118, 1.0, v118
	v_add_f32_e32 v119, 1.0, v119
	v_add_f32_e32 v112, 1.0, v112
	v_add_f32_e32 v113, 1.0, v113
	v_add_f32_e32 v114, 1.0, v114
	v_add_f32_e32 v115, 1.0, v115
	v_rcp_f32_e32 v116, v116
	v_rcp_f32_e32 v117, v117
	v_rcp_f32_e32 v118, v118
	v_rcp_f32_e32 v119, v119
	v_rcp_f32_e32 v112, v112
	v_rcp_f32_e32 v113, v113
	v_rcp_f32_e32 v114, v114
	v_rcp_f32_e32 v115, v115
	v_cvt_pk_bf16_f32 v164, v116, v117
	v_cvt_pk_bf16_f32 v165, v118, v119
	v_cvt_pk_bf16_f32 v166, v112, v113
	s_nop 0
	v_cvt_pk_bf16_f32 v167, v114, v115
	global_store_dwordx4 v[148:149], v[164:167], off offset:256 nt
	s_mov_b32 s100, 0x10000
	v_lshl_add_u64 v[150:151], v[148:149], 0, s[100:101]
	v_mul_f32_e32 v108, 0xbfb8aa3b, v108
	v_mul_f32_e32 v109, 0xbfb8aa3b, v109
	v_mul_f32_e32 v110, 0xbfb8aa3b, v110
	v_mul_f32_e32 v111, 0xbfb8aa3b, v111
	v_mul_f32_e32 v104, 0xbfb8aa3b, v104
	v_mul_f32_e32 v105, 0xbfb8aa3b, v105
	v_mul_f32_e32 v106, 0xbfb8aa3b, v106
	v_mul_f32_e32 v107, 0xbfb8aa3b, v107
	v_exp_f32_e32 v108, v108
	v_exp_f32_e32 v109, v109
	v_exp_f32_e32 v110, v110
	v_exp_f32_e32 v111, v111
	v_exp_f32_e32 v104, v104
	v_exp_f32_e32 v105, v105
	v_exp_f32_e32 v106, v106
	v_exp_f32_e32 v107, v107
	v_add_f32_e32 v108, 1.0, v108
	v_add_f32_e32 v109, 1.0, v109
	v_add_f32_e32 v110, 1.0, v110
	v_add_f32_e32 v111, 1.0, v111
	v_add_f32_e32 v104, 1.0, v104
	v_add_f32_e32 v105, 1.0, v105
	v_add_f32_e32 v106, 1.0, v106
	v_add_f32_e32 v107, 1.0, v107
	v_rcp_f32_e32 v108, v108
	v_rcp_f32_e32 v109, v109
	v_rcp_f32_e32 v110, v110
	v_rcp_f32_e32 v111, v111
	v_rcp_f32_e32 v104, v104
	v_rcp_f32_e32 v105, v105
	v_rcp_f32_e32 v106, v106
	v_rcp_f32_e32 v107, v107
	v_cvt_pk_bf16_f32 v152, v108, v109
	v_cvt_pk_bf16_f32 v153, v110, v111
	v_cvt_pk_bf16_f32 v154, v104, v105
	s_nop 0
	v_cvt_pk_bf16_f32 v155, v106, v107
	global_store_dwordx4 v[150:151], v[152:155], off nt
	v_mul_f32_e32 v100, 0xbfb8aa3b, v100
	v_mul_f32_e32 v101, 0xbfb8aa3b, v101
	v_mul_f32_e32 v102, 0xbfb8aa3b, v102
	v_mul_f32_e32 v103, 0xbfb8aa3b, v103
	v_mul_f32_e32 v96, 0xbfb8aa3b, v96
	v_mul_f32_e32 v97, 0xbfb8aa3b, v97
	v_mul_f32_e32 v98, 0xbfb8aa3b, v98
	v_mul_f32_e32 v99, 0xbfb8aa3b, v99
	v_exp_f32_e32 v100, v100
	v_exp_f32_e32 v101, v101
	v_exp_f32_e32 v102, v102
	v_exp_f32_e32 v103, v103
	v_exp_f32_e32 v96, v96
	v_exp_f32_e32 v97, v97
	v_exp_f32_e32 v98, v98
	v_exp_f32_e32 v99, v99
	v_add_f32_e32 v100, 1.0, v100
	v_add_f32_e32 v101, 1.0, v101
	v_add_f32_e32 v102, 1.0, v102
	v_add_f32_e32 v103, 1.0, v103
	v_add_f32_e32 v96, 1.0, v96
	v_add_f32_e32 v97, 1.0, v97
	v_add_f32_e32 v98, 1.0, v98
	v_add_f32_e32 v99, 1.0, v99
	v_rcp_f32_e32 v100, v100
	v_rcp_f32_e32 v101, v101
	v_rcp_f32_e32 v102, v102
	v_rcp_f32_e32 v103, v103
	v_rcp_f32_e32 v96, v96
	v_rcp_f32_e32 v97, v97
	v_rcp_f32_e32 v98, v98
	v_rcp_f32_e32 v99, v99
	v_cvt_pk_bf16_f32 v164, v100, v101
	v_cvt_pk_bf16_f32 v165, v102, v103
	v_cvt_pk_bf16_f32 v166, v96, v97
	s_nop 0
	v_cvt_pk_bf16_f32 v167, v98, v99
	global_store_dwordx4 v[150:151], v[164:167], off offset:256 nt
	s_mov_b32 s100, 0x20000
	v_lshl_add_u64 v[150:151], v[148:149], 0, s[100:101]
	v_mul_f32_e32 v92, 0xbfb8aa3b, v92
	v_mul_f32_e32 v93, 0xbfb8aa3b, v93
	v_mul_f32_e32 v94, 0xbfb8aa3b, v94
	v_mul_f32_e32 v95, 0xbfb8aa3b, v95
	v_mul_f32_e32 v88, 0xbfb8aa3b, v88
	v_mul_f32_e32 v89, 0xbfb8aa3b, v89
	v_mul_f32_e32 v90, 0xbfb8aa3b, v90
	v_mul_f32_e32 v91, 0xbfb8aa3b, v91
	v_exp_f32_e32 v92, v92
	v_exp_f32_e32 v93, v93
	v_exp_f32_e32 v94, v94
	v_exp_f32_e32 v95, v95
	v_exp_f32_e32 v88, v88
	v_exp_f32_e32 v89, v89
	v_exp_f32_e32 v90, v90
	v_exp_f32_e32 v91, v91
	v_add_f32_e32 v92, 1.0, v92
	v_add_f32_e32 v93, 1.0, v93
	v_add_f32_e32 v94, 1.0, v94
	v_add_f32_e32 v95, 1.0, v95
	v_add_f32_e32 v88, 1.0, v88
	v_add_f32_e32 v89, 1.0, v89
	v_add_f32_e32 v90, 1.0, v90
	v_add_f32_e32 v91, 1.0, v91
	v_rcp_f32_e32 v92, v92
	v_rcp_f32_e32 v93, v93
	v_rcp_f32_e32 v94, v94
	v_rcp_f32_e32 v95, v95
	v_rcp_f32_e32 v88, v88
	v_rcp_f32_e32 v89, v89
	v_rcp_f32_e32 v90, v90
	v_rcp_f32_e32 v91, v91
	v_cvt_pk_bf16_f32 v152, v92, v93
	v_cvt_pk_bf16_f32 v153, v94, v95
	v_cvt_pk_bf16_f32 v154, v88, v89
	s_nop 0
	v_cvt_pk_bf16_f32 v155, v90, v91
	global_store_dwordx4 v[150:151], v[152:155], off nt
	v_mul_f32_e32 v84, 0xbfb8aa3b, v84
	v_mul_f32_e32 v85, 0xbfb8aa3b, v85
	v_mul_f32_e32 v86, 0xbfb8aa3b, v86
	v_mul_f32_e32 v87, 0xbfb8aa3b, v87
	v_mul_f32_e32 v80, 0xbfb8aa3b, v80
	v_mul_f32_e32 v81, 0xbfb8aa3b, v81
	v_mul_f32_e32 v82, 0xbfb8aa3b, v82
	v_mul_f32_e32 v83, 0xbfb8aa3b, v83
	v_exp_f32_e32 v84, v84
	v_exp_f32_e32 v85, v85
	v_exp_f32_e32 v86, v86
	v_exp_f32_e32 v87, v87
	v_exp_f32_e32 v80, v80
	v_exp_f32_e32 v81, v81
	v_exp_f32_e32 v82, v82
	v_exp_f32_e32 v83, v83
	v_add_f32_e32 v84, 1.0, v84
	v_add_f32_e32 v85, 1.0, v85
	v_add_f32_e32 v86, 1.0, v86
	v_add_f32_e32 v87, 1.0, v87
	v_add_f32_e32 v80, 1.0, v80
	v_add_f32_e32 v81, 1.0, v81
	v_add_f32_e32 v82, 1.0, v82
	v_add_f32_e32 v83, 1.0, v83
	v_rcp_f32_e32 v84, v84
	v_rcp_f32_e32 v85, v85
	v_rcp_f32_e32 v86, v86
	v_rcp_f32_e32 v87, v87
	v_rcp_f32_e32 v80, v80
	v_rcp_f32_e32 v81, v81
	v_rcp_f32_e32 v82, v82
	v_rcp_f32_e32 v83, v83
	v_cvt_pk_bf16_f32 v164, v84, v85
	v_cvt_pk_bf16_f32 v165, v86, v87
	v_cvt_pk_bf16_f32 v166, v80, v81
	s_nop 0
	v_cvt_pk_bf16_f32 v167, v82, v83
	global_store_dwordx4 v[150:151], v[164:167], off offset:256 nt
	s_mov_b32 s100, 0x30000
	v_lshl_add_u64 v[150:151], v[148:149], 0, s[100:101]
	v_mul_f32_e32 v76, 0xbfb8aa3b, v76
	v_mul_f32_e32 v77, 0xbfb8aa3b, v77
	v_mul_f32_e32 v78, 0xbfb8aa3b, v78
	v_mul_f32_e32 v79, 0xbfb8aa3b, v79
	v_mul_f32_e32 v72, 0xbfb8aa3b, v72
	v_mul_f32_e32 v73, 0xbfb8aa3b, v73
	v_mul_f32_e32 v74, 0xbfb8aa3b, v74
	v_mul_f32_e32 v75, 0xbfb8aa3b, v75
	v_exp_f32_e32 v76, v76
	v_exp_f32_e32 v77, v77
	v_exp_f32_e32 v78, v78
	v_exp_f32_e32 v79, v79
	v_exp_f32_e32 v72, v72
	v_exp_f32_e32 v73, v73
	v_exp_f32_e32 v74, v74
	v_exp_f32_e32 v75, v75
	v_add_f32_e32 v76, 1.0, v76
	v_add_f32_e32 v77, 1.0, v77
	v_add_f32_e32 v78, 1.0, v78
	v_add_f32_e32 v79, 1.0, v79
	v_add_f32_e32 v72, 1.0, v72
	v_add_f32_e32 v73, 1.0, v73
	v_add_f32_e32 v74, 1.0, v74
	v_add_f32_e32 v75, 1.0, v75
	v_rcp_f32_e32 v76, v76
	v_rcp_f32_e32 v77, v77
	v_rcp_f32_e32 v78, v78
	v_rcp_f32_e32 v79, v79
	v_rcp_f32_e32 v72, v72
	v_rcp_f32_e32 v73, v73
	v_rcp_f32_e32 v74, v74
	v_rcp_f32_e32 v75, v75
	v_cvt_pk_bf16_f32 v152, v76, v77
	v_cvt_pk_bf16_f32 v153, v78, v79
	v_cvt_pk_bf16_f32 v154, v72, v73
	s_nop 0
	v_cvt_pk_bf16_f32 v155, v74, v75
	global_store_dwordx4 v[150:151], v[152:155], off nt
	v_mul_f32_e32 v68, 0xbfb8aa3b, v68
	v_mul_f32_e32 v69, 0xbfb8aa3b, v69
	v_mul_f32_e32 v70, 0xbfb8aa3b, v70
	v_mul_f32_e32 v71, 0xbfb8aa3b, v71
	v_mul_f32_e32 v64, 0xbfb8aa3b, v64
	v_mul_f32_e32 v65, 0xbfb8aa3b, v65
	v_mul_f32_e32 v66, 0xbfb8aa3b, v66
	v_mul_f32_e32 v67, 0xbfb8aa3b, v67
	v_exp_f32_e32 v68, v68
	v_exp_f32_e32 v69, v69
	v_exp_f32_e32 v70, v70
	v_exp_f32_e32 v71, v71
	v_exp_f32_e32 v64, v64
	v_exp_f32_e32 v65, v65
	v_exp_f32_e32 v66, v66
	v_exp_f32_e32 v67, v67
	v_add_f32_e32 v68, 1.0, v68
	v_add_f32_e32 v69, 1.0, v69
	v_add_f32_e32 v70, 1.0, v70
	v_add_f32_e32 v71, 1.0, v71
	v_add_f32_e32 v64, 1.0, v64
	v_add_f32_e32 v65, 1.0, v65
	v_add_f32_e32 v66, 1.0, v66
	v_add_f32_e32 v67, 1.0, v67
	v_rcp_f32_e32 v68, v68
	v_rcp_f32_e32 v69, v69
	v_rcp_f32_e32 v70, v70
	v_rcp_f32_e32 v71, v71
	v_rcp_f32_e32 v64, v64
	v_rcp_f32_e32 v65, v65
	v_rcp_f32_e32 v66, v66
	v_rcp_f32_e32 v67, v67
	v_cvt_pk_bf16_f32 v164, v68, v69
	v_cvt_pk_bf16_f32 v165, v70, v71
	v_cvt_pk_bf16_f32 v166, v64, v65
	s_nop 0
	v_cvt_pk_bf16_f32 v167, v66, v67
	global_store_dwordx4 v[150:151], v[164:167], off offset:256 nt
	s_mov_b32 s100, 0x80000
	v_lshl_add_u64 v[150:151], v[148:149], 0, s[100:101]
	v_mul_f32_e32 v60, 0xbfb8aa3b, v60
	v_mul_f32_e32 v61, 0xbfb8aa3b, v61
	v_mul_f32_e32 v62, 0xbfb8aa3b, v62
	v_mul_f32_e32 v63, 0xbfb8aa3b, v63
	v_mul_f32_e32 v56, 0xbfb8aa3b, v56
	v_mul_f32_e32 v57, 0xbfb8aa3b, v57
	v_mul_f32_e32 v58, 0xbfb8aa3b, v58
	v_mul_f32_e32 v59, 0xbfb8aa3b, v59
	v_exp_f32_e32 v60, v60
	v_exp_f32_e32 v61, v61
	v_exp_f32_e32 v62, v62
	v_exp_f32_e32 v63, v63
	v_exp_f32_e32 v56, v56
	v_exp_f32_e32 v57, v57
	v_exp_f32_e32 v58, v58
	v_exp_f32_e32 v59, v59
	v_add_f32_e32 v60, 1.0, v60
	v_add_f32_e32 v61, 1.0, v61
	v_add_f32_e32 v62, 1.0, v62
	v_add_f32_e32 v63, 1.0, v63
	v_add_f32_e32 v56, 1.0, v56
	v_add_f32_e32 v57, 1.0, v57
	v_add_f32_e32 v58, 1.0, v58
	v_add_f32_e32 v59, 1.0, v59
	v_rcp_f32_e32 v60, v60
	v_rcp_f32_e32 v61, v61
	v_rcp_f32_e32 v62, v62
	v_rcp_f32_e32 v63, v63
	v_rcp_f32_e32 v56, v56
	v_rcp_f32_e32 v57, v57
	v_rcp_f32_e32 v58, v58
	v_rcp_f32_e32 v59, v59
	v_cvt_pk_bf16_f32 v152, v60, v61
	v_cvt_pk_bf16_f32 v153, v62, v63
	v_cvt_pk_bf16_f32 v154, v56, v57
	s_nop 0
	v_cvt_pk_bf16_f32 v155, v58, v59
	global_store_dwordx4 v[150:151], v[152:155], off nt
	v_mul_f32_e32 v52, 0xbfb8aa3b, v52
	v_mul_f32_e32 v53, 0xbfb8aa3b, v53
	v_mul_f32_e32 v54, 0xbfb8aa3b, v54
	v_mul_f32_e32 v55, 0xbfb8aa3b, v55
	v_mul_f32_e32 v48, 0xbfb8aa3b, v48
	v_mul_f32_e32 v49, 0xbfb8aa3b, v49
	v_mul_f32_e32 v50, 0xbfb8aa3b, v50
	v_mul_f32_e32 v51, 0xbfb8aa3b, v51
	v_exp_f32_e32 v52, v52
	v_exp_f32_e32 v53, v53
	v_exp_f32_e32 v54, v54
	v_exp_f32_e32 v55, v55
	v_exp_f32_e32 v48, v48
	v_exp_f32_e32 v49, v49
	v_exp_f32_e32 v50, v50
	v_exp_f32_e32 v51, v51
	v_add_f32_e32 v52, 1.0, v52
	v_add_f32_e32 v53, 1.0, v53
	v_add_f32_e32 v54, 1.0, v54
	v_add_f32_e32 v55, 1.0, v55
	v_add_f32_e32 v48, 1.0, v48
	v_add_f32_e32 v49, 1.0, v49
	v_add_f32_e32 v50, 1.0, v50
	v_add_f32_e32 v51, 1.0, v51
	v_rcp_f32_e32 v52, v52
	v_rcp_f32_e32 v53, v53
	v_rcp_f32_e32 v54, v54
	v_rcp_f32_e32 v55, v55
	v_rcp_f32_e32 v48, v48
	v_rcp_f32_e32 v49, v49
	v_rcp_f32_e32 v50, v50
	v_rcp_f32_e32 v51, v51
	v_cvt_pk_bf16_f32 v164, v52, v53
	v_cvt_pk_bf16_f32 v165, v54, v55
	v_cvt_pk_bf16_f32 v166, v48, v49
	s_nop 0
	v_cvt_pk_bf16_f32 v167, v50, v51
	global_store_dwordx4 v[150:151], v[164:167], off offset:256 nt
	s_mov_b32 s100, 0x90000
	v_lshl_add_u64 v[150:151], v[148:149], 0, s[100:101]
	v_mul_f32_e32 v44, 0xbfb8aa3b, v44
	v_mul_f32_e32 v45, 0xbfb8aa3b, v45
	v_mul_f32_e32 v46, 0xbfb8aa3b, v46
	v_mul_f32_e32 v47, 0xbfb8aa3b, v47
	v_mul_f32_e32 v40, 0xbfb8aa3b, v40
	v_mul_f32_e32 v41, 0xbfb8aa3b, v41
	v_mul_f32_e32 v42, 0xbfb8aa3b, v42
	v_mul_f32_e32 v43, 0xbfb8aa3b, v43
	v_exp_f32_e32 v44, v44
	v_exp_f32_e32 v45, v45
	v_exp_f32_e32 v46, v46
	v_exp_f32_e32 v47, v47
	v_exp_f32_e32 v40, v40
	v_exp_f32_e32 v41, v41
	v_exp_f32_e32 v42, v42
	v_exp_f32_e32 v43, v43
	v_add_f32_e32 v44, 1.0, v44
	v_add_f32_e32 v45, 1.0, v45
	v_add_f32_e32 v46, 1.0, v46
	v_add_f32_e32 v47, 1.0, v47
	v_add_f32_e32 v40, 1.0, v40
	v_add_f32_e32 v41, 1.0, v41
	v_add_f32_e32 v42, 1.0, v42
	v_add_f32_e32 v43, 1.0, v43
	v_rcp_f32_e32 v44, v44
	v_rcp_f32_e32 v45, v45
	v_rcp_f32_e32 v46, v46
	v_rcp_f32_e32 v47, v47
	v_rcp_f32_e32 v40, v40
	v_rcp_f32_e32 v41, v41
	v_rcp_f32_e32 v42, v42
	v_rcp_f32_e32 v43, v43
	v_cvt_pk_bf16_f32 v152, v44, v45
	v_cvt_pk_bf16_f32 v153, v46, v47
	v_cvt_pk_bf16_f32 v154, v40, v41
	s_nop 0
	v_cvt_pk_bf16_f32 v155, v42, v43
	global_store_dwordx4 v[150:151], v[152:155], off nt
	v_mul_f32_e32 v36, 0xbfb8aa3b, v36
	v_mul_f32_e32 v37, 0xbfb8aa3b, v37
	v_mul_f32_e32 v38, 0xbfb8aa3b, v38
	v_mul_f32_e32 v39, 0xbfb8aa3b, v39
	v_mul_f32_e32 v32, 0xbfb8aa3b, v32
	v_mul_f32_e32 v33, 0xbfb8aa3b, v33
	v_mul_f32_e32 v34, 0xbfb8aa3b, v34
	v_mul_f32_e32 v35, 0xbfb8aa3b, v35
	v_exp_f32_e32 v36, v36
	v_exp_f32_e32 v37, v37
	v_exp_f32_e32 v38, v38
	v_exp_f32_e32 v39, v39
	v_exp_f32_e32 v32, v32
	v_exp_f32_e32 v33, v33
	v_exp_f32_e32 v34, v34
	v_exp_f32_e32 v35, v35
	v_add_f32_e32 v36, 1.0, v36
	v_add_f32_e32 v37, 1.0, v37
	v_add_f32_e32 v38, 1.0, v38
	v_add_f32_e32 v39, 1.0, v39
	v_add_f32_e32 v32, 1.0, v32
	v_add_f32_e32 v33, 1.0, v33
	v_add_f32_e32 v34, 1.0, v34
	v_add_f32_e32 v35, 1.0, v35
	v_rcp_f32_e32 v36, v36
	v_rcp_f32_e32 v37, v37
	v_rcp_f32_e32 v38, v38
	v_rcp_f32_e32 v39, v39
	v_rcp_f32_e32 v32, v32
	v_rcp_f32_e32 v33, v33
	v_rcp_f32_e32 v34, v34
	v_rcp_f32_e32 v35, v35
	v_cvt_pk_bf16_f32 v164, v36, v37
	v_cvt_pk_bf16_f32 v165, v38, v39
	v_cvt_pk_bf16_f32 v166, v32, v33
	s_nop 0
	v_cvt_pk_bf16_f32 v167, v34, v35
	global_store_dwordx4 v[150:151], v[164:167], off offset:256 nt
	s_mov_b32 s100, 0xa0000
	v_lshl_add_u64 v[150:151], v[148:149], 0, s[100:101]
	v_mul_f32_e32 v28, 0xbfb8aa3b, v28
	v_mul_f32_e32 v29, 0xbfb8aa3b, v29
	v_mul_f32_e32 v30, 0xbfb8aa3b, v30
	v_mul_f32_e32 v31, 0xbfb8aa3b, v31
	v_mul_f32_e32 v24, 0xbfb8aa3b, v24
	v_mul_f32_e32 v25, 0xbfb8aa3b, v25
	v_mul_f32_e32 v26, 0xbfb8aa3b, v26
	v_mul_f32_e32 v27, 0xbfb8aa3b, v27
	v_exp_f32_e32 v28, v28
	v_exp_f32_e32 v29, v29
	v_exp_f32_e32 v30, v30
	v_exp_f32_e32 v31, v31
	v_exp_f32_e32 v24, v24
	v_exp_f32_e32 v25, v25
	v_exp_f32_e32 v26, v26
	v_exp_f32_e32 v27, v27
	v_add_f32_e32 v28, 1.0, v28
	v_add_f32_e32 v29, 1.0, v29
	v_add_f32_e32 v30, 1.0, v30
	v_add_f32_e32 v31, 1.0, v31
	v_add_f32_e32 v24, 1.0, v24
	v_add_f32_e32 v25, 1.0, v25
	v_add_f32_e32 v26, 1.0, v26
	v_add_f32_e32 v27, 1.0, v27
	v_rcp_f32_e32 v28, v28
	v_rcp_f32_e32 v29, v29
	v_rcp_f32_e32 v30, v30
	v_rcp_f32_e32 v31, v31
	v_rcp_f32_e32 v24, v24
	v_rcp_f32_e32 v25, v25
	v_rcp_f32_e32 v26, v26
	v_rcp_f32_e32 v27, v27
	v_cvt_pk_bf16_f32 v152, v28, v29
	v_cvt_pk_bf16_f32 v153, v30, v31
	v_cvt_pk_bf16_f32 v154, v24, v25
	s_nop 0
	v_cvt_pk_bf16_f32 v155, v26, v27
	global_store_dwordx4 v[150:151], v[152:155], off nt
	v_mul_f32_e32 v20, 0xbfb8aa3b, v20
	v_mul_f32_e32 v21, 0xbfb8aa3b, v21
	v_mul_f32_e32 v22, 0xbfb8aa3b, v22
	v_mul_f32_e32 v23, 0xbfb8aa3b, v23
	v_mul_f32_e32 v16, 0xbfb8aa3b, v16
	v_mul_f32_e32 v17, 0xbfb8aa3b, v17
	v_mul_f32_e32 v18, 0xbfb8aa3b, v18
	v_mul_f32_e32 v19, 0xbfb8aa3b, v19
	v_exp_f32_e32 v20, v20
	v_exp_f32_e32 v21, v21
	v_exp_f32_e32 v22, v22
	v_exp_f32_e32 v23, v23
	v_exp_f32_e32 v16, v16
	v_exp_f32_e32 v17, v17
	v_exp_f32_e32 v18, v18
	v_exp_f32_e32 v19, v19
	v_add_f32_e32 v20, 1.0, v20
	v_add_f32_e32 v21, 1.0, v21
	v_add_f32_e32 v22, 1.0, v22
	v_add_f32_e32 v23, 1.0, v23
	v_add_f32_e32 v16, 1.0, v16
	v_add_f32_e32 v17, 1.0, v17
	v_add_f32_e32 v18, 1.0, v18
	v_add_f32_e32 v19, 1.0, v19
	v_rcp_f32_e32 v20, v20
	v_rcp_f32_e32 v21, v21
	v_rcp_f32_e32 v22, v22
	v_rcp_f32_e32 v23, v23
	v_rcp_f32_e32 v16, v16
	v_rcp_f32_e32 v17, v17
	v_rcp_f32_e32 v18, v18
	v_rcp_f32_e32 v19, v19
	v_cvt_pk_bf16_f32 v164, v20, v21
	v_cvt_pk_bf16_f32 v165, v22, v23
	v_cvt_pk_bf16_f32 v166, v16, v17
	s_nop 0
	v_cvt_pk_bf16_f32 v167, v18, v19
	global_store_dwordx4 v[150:151], v[164:167], off offset:256 nt
	s_mov_b32 s100, 0xb0000
	v_lshl_add_u64 v[150:151], v[148:149], 0, s[100:101]
	v_mul_f32_e32 v12, 0xbfb8aa3b, v12
	v_mul_f32_e32 v13, 0xbfb8aa3b, v13
	v_mul_f32_e32 v14, 0xbfb8aa3b, v14
	v_mul_f32_e32 v15, 0xbfb8aa3b, v15
	v_mul_f32_e32 v8, 0xbfb8aa3b, v8
	v_mul_f32_e32 v9, 0xbfb8aa3b, v9
	v_mul_f32_e32 v10, 0xbfb8aa3b, v10
	v_mul_f32_e32 v11, 0xbfb8aa3b, v11
	v_exp_f32_e32 v12, v12
	v_exp_f32_e32 v13, v13
	v_exp_f32_e32 v14, v14
	v_exp_f32_e32 v15, v15
	v_exp_f32_e32 v8, v8
	v_exp_f32_e32 v9, v9
	v_exp_f32_e32 v10, v10
	v_exp_f32_e32 v11, v11
	v_add_f32_e32 v12, 1.0, v12
	v_add_f32_e32 v13, 1.0, v13
	v_add_f32_e32 v14, 1.0, v14
	v_add_f32_e32 v15, 1.0, v15
	v_add_f32_e32 v8, 1.0, v8
	v_add_f32_e32 v9, 1.0, v9
	v_add_f32_e32 v10, 1.0, v10
	v_add_f32_e32 v11, 1.0, v11
	v_rcp_f32_e32 v12, v12
	v_rcp_f32_e32 v13, v13
	v_rcp_f32_e32 v14, v14
	v_rcp_f32_e32 v15, v15
	v_rcp_f32_e32 v8, v8
	v_rcp_f32_e32 v9, v9
	v_rcp_f32_e32 v10, v10
	v_rcp_f32_e32 v11, v11
	v_cvt_pk_bf16_f32 v152, v12, v13
	v_cvt_pk_bf16_f32 v153, v14, v15
	v_cvt_pk_bf16_f32 v154, v8, v9
	s_nop 0
	v_cvt_pk_bf16_f32 v155, v10, v11
	global_store_dwordx4 v[150:151], v[152:155], off nt
	v_mul_f32_e32 v4, 0xbfb8aa3b, v4
	v_mul_f32_e32 v5, 0xbfb8aa3b, v5
	v_mul_f32_e32 v6, 0xbfb8aa3b, v6
	v_mul_f32_e32 v7, 0xbfb8aa3b, v7
	v_mul_f32_e32 v0, 0xbfb8aa3b, v0
	v_mul_f32_e32 v1, 0xbfb8aa3b, v1
	v_mul_f32_e32 v2, 0xbfb8aa3b, v2
	v_mul_f32_e32 v3, 0xbfb8aa3b, v3
	v_exp_f32_e32 v4, v4
	v_exp_f32_e32 v5, v5
	v_exp_f32_e32 v6, v6
	v_exp_f32_e32 v7, v7
	v_exp_f32_e32 v0, v0
	v_exp_f32_e32 v1, v1
	v_exp_f32_e32 v2, v2
	v_exp_f32_e32 v3, v3
	v_add_f32_e32 v4, 1.0, v4
	v_add_f32_e32 v5, 1.0, v5
	v_add_f32_e32 v6, 1.0, v6
	v_add_f32_e32 v7, 1.0, v7
	v_add_f32_e32 v0, 1.0, v0
	v_add_f32_e32 v1, 1.0, v1
	v_add_f32_e32 v2, 1.0, v2
	v_add_f32_e32 v3, 1.0, v3
	v_rcp_f32_e32 v4, v4
	v_rcp_f32_e32 v5, v5
	v_rcp_f32_e32 v6, v6
	v_rcp_f32_e32 v7, v7
	v_rcp_f32_e32 v0, v0
	v_rcp_f32_e32 v1, v1
	v_rcp_f32_e32 v2, v2
	v_rcp_f32_e32 v3, v3
	v_cvt_pk_bf16_f32 v164, v4, v5
	v_cvt_pk_bf16_f32 v165, v6, v7
	v_cvt_pk_bf16_f32 v166, v0, v1
	s_nop 0
	v_cvt_pk_bf16_f32 v167, v2, v3
	global_store_dwordx4 v[150:151], v[164:167], off offset:256 nt
	s_branch .Luhy_join
